# grid barrier pollers: s_sleep 3 instead of 1 between polls of the per-XCD generation word (less polling traffic against straggler stores)
# baseline (speedup 1.0000x reference)
.LBB0_847:
	s_and_b32 s18, s22, 0xff
	s_mov_b64 s[16:17], -1
	s_cmp_lg_u32 s18, 0
	s_mov_b64 s[20:21], -1
	s_sleep 3
	s_cbranch_scc0 .LBB0_850
	s_and_b64 vcc, exec, s[20:21]
	s_cbranch_vccz .LBB0_846
